# P4: lru_scan runs on workgroups 248-255 instead of 0-7 so it no longer serialises behind the mLSTM n-state scan on workgroups 0-1
# baseline (speedup 1.0000x reference)
.LBB0_1078:
	s_or_b64 exec, exec, s[6:7]
	s_mov_b64 s[10:11], s[62:63]
	v_mov_b32_e32 v0, v208
	s_nop 0
	v_add_u32_e32 v6, s61, v0
	v_subrev_u32_e32 v6, 0x1f000, v6
	v_cmp_gt_u32_e32 vcc, s91, v6
	s_and_saveexec_b64 s[6:7], vcc
	s_cbranch_execz .LBB0_1081
	s_load_dwordx2 s[12:13], s[10:11], 0xc0
	v_and_b32_e32 v7, 0x1ff, v0
	v_lshlrev_b32_e32 v166, 2, v7
	s_mov_b64 s[2:3], 0x7442800
	s_mov_b64 s[10:11], 0
	s_waitcnt lgkmcnt(0)
	v_mov_b32_e32 v2, s12
	v_mov_b32_e32 v3, s13
	v_lshl_add_u64 v[0:1], v[2:3], 0, s[2:3]
	v_lshl_add_u64 v[2:3], v[2:3], 0, v[166:167]
	s_mov_b64 s[2:3], 0x2a4c2800
	v_lshl_add_u64 v[2:3], v[2:3], 0, s[2:3]
